# grid barrier: XCC leaders poll the cross-XCC arrival counter itself (no separate generation word), one atomic hop fewer per barrier
# speedup vs baseline: 1.0095x; 1.0095x over previous
; #define GSYNC() do { ++bar_n; grid_barrier(bar_ctr, bar_n * (unsigned)G); } while (0)
; __device__ __forceinline__ void grid_barrier(unsigned* ctr, unsigned target) {
;     asm volatile("s_waitcnt vmcnt(0)" ::: "memory");
;     __syncthreads();
;     if (threadIdx.x == 0) {
;         __builtin_amdgcn_fence(__ATOMIC_RELEASE, "agent");
;         asm volatile("s_waitcnt vmcnt(0)" ::: "memory");
;         __hip_atomic_fetch_add(ctr, 1u, __ATOMIC_RELAXED, __HIP_MEMORY_SCOPE_AGENT);
;         unsigned spins = 0;
;         while (__hip_atomic_load(ctr, __ATOMIC_RELAXED, __HIP_MEMORY_SCOPE_AGENT) < target) { __builtin_amdgcn_s_sleep(2); if (++spins > (1u << 24)) break; }
;         __builtin_amdgcn_fence(__ATOMIC_ACQUIRE, "agent");
;         asm volatile("s_waitcnt vmcnt(0)" ::: "memory");
;     }
;     __syncthreads();
; }
; __global__ void __launch_bounds__(512, 2) mk_fwd(Args a) {
;     ...
;     GSYNC();
.LBB0_65:
	s_waitcnt vmcnt(0)
	s_waitcnt lgkmcnt(0)
	s_barrier
	s_mov_b64 s[4:5], exec
	v_readlane_b32 s0, v255, 0
	v_readlane_b32 s1, v255, 1
	s_and_b64 s[0:1], s[4:5], s[0:1]
	s_mov_b64 exec, s[0:1]
	s_cbranch_execz .LBB0_82
	s_getreg_b32 s6, hwreg(HW_REG_XCC_ID, 0, 4)
	s_and_b32 s6, s6, 7
	s_lshl_b32 s6, s6, 8
	s_add_i32 s7, s6, 0x16000
	v_mov_b32_e32 v0, s7
	v_mov_b32_e32 v1, 1
	global_atomic_add v1, v0, v1, s[22:23] sc0
	s_waitcnt vmcnt(0)
	v_readfirstlane_b32 s7, v1
	s_nop 1
	s_add_i32 s7, s7, 1
	s_cmp_lg_u32 s7, 32
	s_cbranch_scc1 .Lmy_gb1_follow
	buffer_wbl2 sc1
	s_waitcnt vmcnt(0)
	v_mov_b32_e32 v0, 0x18000
	v_mov_b32_e32 v1, 1
	global_atomic_add v1, v0, v1, s[22:23] sc0
	s_waitcnt vmcnt(0)
	v_readfirstlane_b32 s7, v1
	s_nop 1
	s_add_i32 s7, s7, 1
	s_cmp_lg_u32 s7, 8
	s_cbranch_scc0 .Lmy_gb1_rel

; __device__ __forceinline__ void grid_barrier(unsigned* ctr, unsigned target) {
;     ...
;         while (__hip_atomic_load(ctr, __ATOMIC_RELAXED, __HIP_MEMORY_SCOPE_AGENT) < target) { __builtin_amdgcn_s_sleep(2); if (++spins > (1u << 24)) break; }
;         __builtin_amdgcn_fence(__ATOMIC_ACQUIRE, "agent");
.Lmy_gb1_topspin:
	global_load_dword v1, v0, s[22:23] sc1
	s_waitcnt vmcnt(0)
	v_readfirstlane_b32 s7, v1
	s_nop 1
	s_cmp_ge_u32 s7, 8
	s_cbranch_scc1 .Lmy_gb1_rel
	s_sleep 1
	s_add_i32 s8, s8, -1
	s_cmp_lg_u32 s8, 0
	s_cbranch_scc1 .Lmy_gb1_topspin

; #define GSYNC() do { ++bar_n; grid_barrier(bar_ctr, bar_n * (unsigned)G); } while (0)
; __device__ __forceinline__ void grid_barrier(unsigned* ctr, unsigned target) {
;     asm volatile("s_waitcnt vmcnt(0)" ::: "memory");
;     __syncthreads();
;     if (threadIdx.x == 0) {
;         __builtin_amdgcn_fence(__ATOMIC_RELEASE, "agent");
;         asm volatile("s_waitcnt vmcnt(0)" ::: "memory");
;         __hip_atomic_fetch_add(ctr, 1u, __ATOMIC_RELAXED, __HIP_MEMORY_SCOPE_AGENT);
;         unsigned spins = 0;
;         while (__hip_atomic_load(ctr, __ATOMIC_RELAXED, __HIP_MEMORY_SCOPE_AGENT) < target) { __builtin_amdgcn_s_sleep(2); if (++spins > (1u << 24)) break; }
;         __builtin_amdgcn_fence(__ATOMIC_ACQUIRE, "agent");
;         asm volatile("s_waitcnt vmcnt(0)" ::: "memory");
;     }
;     __syncthreads();
; }
; __global__ void __launch_bounds__(512, 2) mk_fwd(Args a) {
;     ...
;     GSYNC();
.LBB0_117:
	s_waitcnt vmcnt(0)
	v_readlane_b32 s4, v255, 0
	v_readlane_b32 s5, v255, 1
	s_waitcnt vmcnt(0) lgkmcnt(0)
	s_barrier
	s_and_saveexec_b64 s[0:1], s[4:5]
	s_xor_b64 s[4:5], exec, s[0:1]
	s_cbranch_execz .LBB0_134
	s_getreg_b32 s6, hwreg(HW_REG_XCC_ID, 0, 4)
	s_and_b32 s6, s6, 7
	s_lshl_b32 s6, s6, 8
	s_add_i32 s7, s6, 0x16000
	v_mov_b32_e32 v0, s7
	v_mov_b32_e32 v1, 1
	global_atomic_add v1, v0, v1, s[22:23] sc0
	s_waitcnt vmcnt(0)
	v_readfirstlane_b32 s7, v1
	s_nop 1
	s_add_i32 s7, s7, 1
	s_cmp_lg_u32 s7, 64
	s_cbranch_scc1 .Lmy_gb2_follow
	buffer_wbl2 sc1
	s_waitcnt vmcnt(0)
	v_mov_b32_e32 v0, 0x18000
	v_mov_b32_e32 v1, 1
	global_atomic_add v1, v0, v1, s[22:23] sc0
	s_waitcnt vmcnt(0)
	v_readfirstlane_b32 s7, v1
	s_nop 1
	s_add_i32 s7, s7, 1
	s_cmp_lg_u32 s7, 16
	s_cbranch_scc0 .Lmy_gb2_rel

; __device__ __forceinline__ void grid_barrier(unsigned* ctr, unsigned target) {
;     ...
;         while (__hip_atomic_load(ctr, __ATOMIC_RELAXED, __HIP_MEMORY_SCOPE_AGENT) < target) { __builtin_amdgcn_s_sleep(2); if (++spins > (1u << 24)) break; }
;         __builtin_amdgcn_fence(__ATOMIC_ACQUIRE, "agent");
.Lmy_gb2_topspin:
	global_load_dword v1, v0, s[22:23] sc1
	s_waitcnt vmcnt(0)
	v_readfirstlane_b32 s7, v1
	s_nop 1
	s_cmp_ge_u32 s7, 16
	s_cbranch_scc1 .Lmy_gb2_rel
	s_sleep 1
	s_add_i32 s8, s8, -1
	s_cmp_lg_u32 s8, 0
	s_cbranch_scc1 .Lmy_gb2_topspin

; #define GSYNC() do { ++bar_n; grid_barrier(bar_ctr, bar_n * (unsigned)G); } while (0)
; __device__ __forceinline__ void grid_barrier(unsigned* ctr, unsigned target) {
;     asm volatile("s_waitcnt vmcnt(0)" ::: "memory");
;     __syncthreads();
;     if (threadIdx.x == 0) {
;         __builtin_amdgcn_fence(__ATOMIC_RELEASE, "agent");
;         asm volatile("s_waitcnt vmcnt(0)" ::: "memory");
;         __hip_atomic_fetch_add(ctr, 1u, __ATOMIC_RELAXED, __HIP_MEMORY_SCOPE_AGENT);
;         unsigned spins = 0;
;         while (__hip_atomic_load(ctr, __ATOMIC_RELAXED, __HIP_MEMORY_SCOPE_AGENT) < target) { __builtin_amdgcn_s_sleep(2); if (++spins > (1u << 24)) break; }
;         __builtin_amdgcn_fence(__ATOMIC_ACQUIRE, "agent");
;         asm volatile("s_waitcnt vmcnt(0)" ::: "memory");
;     }
;     __syncthreads();
; }
; __global__ void __launch_bounds__(512, 2) mk_fwd(Args a) {
;     ...
;     GSYNC();
.LBB0_255:
	s_waitcnt vmcnt(0)
	v_readlane_b32 s4, v255, 0
	v_readlane_b32 s5, v255, 1
	s_barrier
	s_and_saveexec_b64 s[0:1], s[4:5]
	s_xor_b64 s[4:5], exec, s[0:1]
	s_cbranch_execz .LBB0_272
	s_getreg_b32 s6, hwreg(HW_REG_XCC_ID, 0, 4)
	s_and_b32 s6, s6, 7
	s_lshl_b32 s6, s6, 8
	s_add_i32 s7, s6, 0x16000
	v_mov_b32_e32 v0, s7
	v_mov_b32_e32 v1, 1
	global_atomic_add v1, v0, v1, s[22:23] sc0
	s_waitcnt vmcnt(0)
	v_readfirstlane_b32 s7, v1
	s_nop 1
	s_add_i32 s7, s7, 1
	s_cmp_lg_u32 s7, 96
	s_cbranch_scc1 .Lmy_gb3_follow
	buffer_wbl2 sc1
	s_waitcnt vmcnt(0)
	v_mov_b32_e32 v0, 0x18000
	v_mov_b32_e32 v1, 1
	global_atomic_add v1, v0, v1, s[22:23] sc0
	s_waitcnt vmcnt(0)
	v_readfirstlane_b32 s7, v1
	s_nop 1
	s_add_i32 s7, s7, 1
	s_cmp_lg_u32 s7, 24
	s_cbranch_scc0 .Lmy_gb3_rel

; __device__ __forceinline__ void grid_barrier(unsigned* ctr, unsigned target) {
;     ...
;         while (__hip_atomic_load(ctr, __ATOMIC_RELAXED, __HIP_MEMORY_SCOPE_AGENT) < target) { __builtin_amdgcn_s_sleep(2); if (++spins > (1u << 24)) break; }
;         __builtin_amdgcn_fence(__ATOMIC_ACQUIRE, "agent");
.Lmy_gb3_topspin:
	global_load_dword v1, v0, s[22:23] sc1
	s_waitcnt vmcnt(0)
	v_readfirstlane_b32 s7, v1
	s_nop 1
	s_cmp_ge_u32 s7, 24
	s_cbranch_scc1 .Lmy_gb3_rel
	s_sleep 1
	s_add_i32 s8, s8, -1
	s_cmp_lg_u32 s8, 0
	s_cbranch_scc1 .Lmy_gb3_topspin

; #define GSYNC() do { ++bar_n; grid_barrier(bar_ctr, bar_n * (unsigned)G); } while (0)
; __device__ __forceinline__ void grid_barrier(unsigned* ctr, unsigned target) {
;     asm volatile("s_waitcnt vmcnt(0)" ::: "memory");
;     __syncthreads();
;     if (threadIdx.x == 0) {
;         __builtin_amdgcn_fence(__ATOMIC_RELEASE, "agent");
;         asm volatile("s_waitcnt vmcnt(0)" ::: "memory");
;         __hip_atomic_fetch_add(ctr, 1u, __ATOMIC_RELAXED, __HIP_MEMORY_SCOPE_AGENT);
;         unsigned spins = 0;
;         while (__hip_atomic_load(ctr, __ATOMIC_RELAXED, __HIP_MEMORY_SCOPE_AGENT) < target) { __builtin_amdgcn_s_sleep(2); if (++spins > (1u << 24)) break; }
;         __builtin_amdgcn_fence(__ATOMIC_ACQUIRE, "agent");
;         asm volatile("s_waitcnt vmcnt(0)" ::: "memory");
;     }
;     __syncthreads();
; }
; __global__ void __launch_bounds__(512, 2) mk_fwd(Args a) {
;     ...
;     GSYNC();
.LBB0_275:
	s_or_b64 exec, exec, s[2:3]
	s_waitcnt vmcnt(0)
	s_barrier
	s_mov_b64 s[2:3], exec
	v_readlane_b32 s0, v255, 0
	v_readlane_b32 s1, v255, 1
	s_and_b64 s[0:1], s[2:3], s[0:1]
	s_mov_b64 exec, s[0:1]
	s_cbranch_execz .LBB0_292
	s_getreg_b32 s4, hwreg(HW_REG_XCC_ID, 0, 4)
	s_and_b32 s4, s4, 7
	s_lshl_b32 s4, s4, 8
	s_add_i32 s5, s4, 0x16000
	v_mov_b32_e32 v0, s5
	v_mov_b32_e32 v1, 1
	global_atomic_add v1, v0, v1, s[22:23] sc0
	s_waitcnt vmcnt(0)
	v_readfirstlane_b32 s5, v1
	s_nop 1
	s_add_i32 s5, s5, 1
	s_cmp_lg_u32 s5, 128
	s_cbranch_scc1 .Lmy_gb4_follow
	buffer_wbl2 sc1
	s_waitcnt vmcnt(0)
	v_mov_b32_e32 v0, 0x18000
	v_mov_b32_e32 v1, 1
	global_atomic_add v1, v0, v1, s[22:23] sc0
	s_waitcnt vmcnt(0)
	v_readfirstlane_b32 s5, v1
	s_nop 1
	s_add_i32 s5, s5, 1
	s_cmp_lg_u32 s5, 32
	s_cbranch_scc0 .Lmy_gb4_rel

; __device__ __forceinline__ void grid_barrier(unsigned* ctr, unsigned target) {
;     ...
;         while (__hip_atomic_load(ctr, __ATOMIC_RELAXED, __HIP_MEMORY_SCOPE_AGENT) < target) { __builtin_amdgcn_s_sleep(2); if (++spins > (1u << 24)) break; }
;         __builtin_amdgcn_fence(__ATOMIC_ACQUIRE, "agent");
.Lmy_gb4_topspin:
	global_load_dword v1, v0, s[22:23] sc1
	s_waitcnt vmcnt(0)
	v_readfirstlane_b32 s5, v1
	s_nop 1
	s_cmp_ge_u32 s5, 32
	s_cbranch_scc1 .Lmy_gb4_rel
	s_sleep 1
	s_add_i32 s6, s6, -1
	s_cmp_lg_u32 s6, 0
	s_cbranch_scc1 .Lmy_gb4_topspin

; #define GSYNC() do { ++bar_n; grid_barrier(bar_ctr, bar_n * (unsigned)G); } while (0)
; __device__ __forceinline__ void grid_barrier(unsigned* ctr, unsigned target) {
;     asm volatile("s_waitcnt vmcnt(0)" ::: "memory");
;     __syncthreads();
;     if (threadIdx.x == 0) {
;         __builtin_amdgcn_fence(__ATOMIC_RELEASE, "agent");
;         asm volatile("s_waitcnt vmcnt(0)" ::: "memory");
;         __hip_atomic_fetch_add(ctr, 1u, __ATOMIC_RELAXED, __HIP_MEMORY_SCOPE_AGENT);
;         unsigned spins = 0;
;         while (__hip_atomic_load(ctr, __ATOMIC_RELAXED, __HIP_MEMORY_SCOPE_AGENT) < target) { __builtin_amdgcn_s_sleep(2); if (++spins > (1u << 24)) break; }
;         __builtin_amdgcn_fence(__ATOMIC_ACQUIRE, "agent");
;         asm volatile("s_waitcnt vmcnt(0)" ::: "memory");
;     }
;     __syncthreads();
; }
; __global__ void __launch_bounds__(512, 2) mk_fwd(Args a) {
;     ...
;     GSYNC();
.LBB0_314:
	s_waitcnt vmcnt(0)
	s_barrier
	s_mov_b64 s[2:3], exec
	v_readlane_b32 s0, v255, 0
	v_readlane_b32 s1, v255, 1
	s_and_b64 s[0:1], s[2:3], s[0:1]
	s_mov_b64 exec, s[0:1]
	s_cbranch_execz .LBB0_331
	s_getreg_b32 s4, hwreg(HW_REG_XCC_ID, 0, 4)
	s_and_b32 s4, s4, 7
	s_lshl_b32 s4, s4, 8
	s_add_i32 s5, s4, 0x16000
	v_mov_b32_e32 v0, s5
	v_mov_b32_e32 v1, 1
	global_atomic_add v1, v0, v1, s[22:23] sc0
	s_waitcnt vmcnt(0)
	v_readfirstlane_b32 s5, v1
	s_nop 1
	s_add_i32 s5, s5, 1
	s_cmp_lg_u32 s5, 160
	s_cbranch_scc1 .Lmy_gb5_follow
	buffer_wbl2 sc1
	s_waitcnt vmcnt(0)
	v_mov_b32_e32 v0, 0x18000
	v_mov_b32_e32 v1, 1
	global_atomic_add v1, v0, v1, s[22:23] sc0
	s_waitcnt vmcnt(0)
	v_readfirstlane_b32 s5, v1
	s_nop 1
	s_add_i32 s5, s5, 1
	s_cmp_lg_u32 s5, 40
	s_cbranch_scc0 .Lmy_gb5_rel

; __device__ __forceinline__ void grid_barrier(unsigned* ctr, unsigned target) {
;     ...
;         while (__hip_atomic_load(ctr, __ATOMIC_RELAXED, __HIP_MEMORY_SCOPE_AGENT) < target) { __builtin_amdgcn_s_sleep(2); if (++spins > (1u << 24)) break; }
;         __builtin_amdgcn_fence(__ATOMIC_ACQUIRE, "agent");
.Lmy_gb5_topspin:
	global_load_dword v1, v0, s[22:23] sc1
	s_waitcnt vmcnt(0)
	v_readfirstlane_b32 s5, v1
	s_nop 1
	s_cmp_ge_u32 s5, 40
	s_cbranch_scc1 .Lmy_gb5_rel
	s_sleep 1
	s_add_i32 s8, s8, -1
	s_cmp_lg_u32 s8, 0
	s_cbranch_scc1 .Lmy_gb5_topspin

; #define GSYNC() do { ++bar_n; grid_barrier(bar_ctr, bar_n * (unsigned)G); } while (0)
; __device__ __forceinline__ void grid_barrier(unsigned* ctr, unsigned target) {
;     asm volatile("s_waitcnt vmcnt(0)" ::: "memory");
;     __syncthreads();
;     if (threadIdx.x == 0) {
;         __builtin_amdgcn_fence(__ATOMIC_RELEASE, "agent");
;         asm volatile("s_waitcnt vmcnt(0)" ::: "memory");
;         __hip_atomic_fetch_add(ctr, 1u, __ATOMIC_RELAXED, __HIP_MEMORY_SCOPE_AGENT);
;         unsigned spins = 0;
;         while (__hip_atomic_load(ctr, __ATOMIC_RELAXED, __HIP_MEMORY_SCOPE_AGENT) < target) { __builtin_amdgcn_s_sleep(2); if (++spins > (1u << 24)) break; }
;         __builtin_amdgcn_fence(__ATOMIC_ACQUIRE, "agent");
;         asm volatile("s_waitcnt vmcnt(0)" ::: "memory");
;     }
;     __syncthreads();
; }
; __global__ void __launch_bounds__(512, 2) mk_fwd(Args a) {
;     ...
;     GSYNC();
.LBB0_365:
	s_waitcnt vmcnt(0)
	v_readlane_b32 s4, v255, 0
	v_readlane_b32 s5, v255, 1
	s_waitcnt lgkmcnt(0)
	s_barrier
	s_and_saveexec_b64 s[0:1], s[4:5]
	s_xor_b64 s[4:5], exec, s[0:1]
	s_cbranch_execz .LBB0_382
	s_getreg_b32 s6, hwreg(HW_REG_XCC_ID, 0, 4)
	s_and_b32 s6, s6, 7
	s_lshl_b32 s6, s6, 8
	s_add_i32 s7, s6, 0x16000
	v_mov_b32_e32 v0, s7
	v_mov_b32_e32 v1, 1
	global_atomic_add v1, v0, v1, s[22:23] sc0
	s_waitcnt vmcnt(0)
	v_readfirstlane_b32 s7, v1
	s_nop 1
	s_add_i32 s7, s7, 1
	s_cmp_lg_u32 s7, 192
	s_cbranch_scc1 .Lmy_gb6_follow
	buffer_wbl2 sc1
	s_waitcnt vmcnt(0)
	v_mov_b32_e32 v0, 0x18000
	v_mov_b32_e32 v1, 1
	global_atomic_add v1, v0, v1, s[22:23] sc0
	s_waitcnt vmcnt(0)
	v_readfirstlane_b32 s7, v1
	s_nop 1
	s_add_i32 s7, s7, 1
	s_cmp_lg_u32 s7, 48
	s_cbranch_scc0 .Lmy_gb6_rel

; __device__ __forceinline__ void grid_barrier(unsigned* ctr, unsigned target) {
;     ...
;         while (__hip_atomic_load(ctr, __ATOMIC_RELAXED, __HIP_MEMORY_SCOPE_AGENT) < target) { __builtin_amdgcn_s_sleep(2); if (++spins > (1u << 24)) break; }
;         __builtin_amdgcn_fence(__ATOMIC_ACQUIRE, "agent");
.Lmy_gb6_topspin:
	global_load_dword v1, v0, s[22:23] sc1
	s_waitcnt vmcnt(0)
	v_readfirstlane_b32 s7, v1
	s_nop 1
	s_cmp_ge_u32 s7, 48
	s_cbranch_scc1 .Lmy_gb6_rel
	s_sleep 1
	s_add_i32 s8, s8, -1
	s_cmp_lg_u32 s8, 0
	s_cbranch_scc1 .Lmy_gb6_topspin

; #define GSYNC() do { ++bar_n; grid_barrier(bar_ctr, bar_n * (unsigned)G); } while (0)
; __device__ __forceinline__ void grid_barrier(unsigned* ctr, unsigned target) {
;     asm volatile("s_waitcnt vmcnt(0)" ::: "memory");
;     __syncthreads();
;     if (threadIdx.x == 0) {
;         __builtin_amdgcn_fence(__ATOMIC_RELEASE, "agent");
;         asm volatile("s_waitcnt vmcnt(0)" ::: "memory");
;         __hip_atomic_fetch_add(ctr, 1u, __ATOMIC_RELAXED, __HIP_MEMORY_SCOPE_AGENT);
;         unsigned spins = 0;
;         while (__hip_atomic_load(ctr, __ATOMIC_RELAXED, __HIP_MEMORY_SCOPE_AGENT) < target) { __builtin_amdgcn_s_sleep(2); if (++spins > (1u << 24)) break; }
;         __builtin_amdgcn_fence(__ATOMIC_ACQUIRE, "agent");
;         asm volatile("s_waitcnt vmcnt(0)" ::: "memory");
;     }
;     __syncthreads();
; }
; __global__ void __launch_bounds__(512, 2) mk_fwd(Args a) {
;     ...
;     GSYNC();
.LBB0_398:
	s_waitcnt vmcnt(0)
	s_barrier
	s_mov_b64 s[0:1], exec
	v_readlane_b32 s4, v255, 0
	v_readlane_b32 s5, v255, 1
	s_and_b64 s[4:5], s[0:1], s[4:5]
	s_xor_b64 s[0:1], s[4:5], s[0:1]
	s_mov_b64 exec, s[4:5]
	s_cbranch_execz .LBB0_415
	s_getreg_b32 s4, hwreg(HW_REG_XCC_ID, 0, 4)
	s_and_b32 s4, s4, 7
	s_lshl_b32 s4, s4, 8
	s_add_i32 s5, s4, 0x16000
	v_mov_b32_e32 v0, s5
	v_mov_b32_e32 v1, 1
	global_atomic_add v1, v0, v1, s[22:23] sc0
	s_waitcnt vmcnt(0)
	v_readfirstlane_b32 s5, v1
	s_nop 1
	s_add_i32 s5, s5, 1
	s_cmp_lg_u32 s5, 224
	s_cbranch_scc1 .Lmy_gb7_follow
	buffer_wbl2 sc1
	s_waitcnt vmcnt(0)
	v_mov_b32_e32 v0, 0x18000
	v_mov_b32_e32 v1, 1
	global_atomic_add v1, v0, v1, s[22:23] sc0
	s_waitcnt vmcnt(0)
	v_readfirstlane_b32 s5, v1
	s_nop 1
	s_add_i32 s5, s5, 1
	s_cmp_lg_u32 s5, 56
	s_cbranch_scc0 .Lmy_gb7_rel

; __device__ __forceinline__ void grid_barrier(unsigned* ctr, unsigned target) {
;     asm volatile("s_waitcnt vmcnt(0)" ::: "memory");
;     __syncthreads();
;     if (threadIdx.x == 0) {
;         __builtin_amdgcn_fence(__ATOMIC_RELEASE, "agent");
;         asm volatile("s_waitcnt vmcnt(0)" ::: "memory");
;         __hip_atomic_fetch_add(ctr, 1u, __ATOMIC_RELAXED, __HIP_MEMORY_SCOPE_AGENT);
;         unsigned spins = 0;
;         while (__hip_atomic_load(ctr, __ATOMIC_RELAXED, __HIP_MEMORY_SCOPE_AGENT) < target) { __builtin_amdgcn_s_sleep(2); if (++spins > (1u << 24)) break; }
;         __builtin_amdgcn_fence(__ATOMIC_ACQUIRE, "agent");
;         asm volatile("s_waitcnt vmcnt(0)" ::: "memory");
;     }
;     __syncthreads();
; }
.Lmy_gb7_topspin:
	global_load_dword v1, v0, s[22:23] sc1
	s_waitcnt vmcnt(0)
	v_readfirstlane_b32 s5, v1
	s_nop 1
	s_cmp_ge_u32 s5, 56
	s_cbranch_scc1 .Lmy_gb7_rel
	s_sleep 1
	s_add_i32 s6, s6, -1
	s_cmp_lg_u32 s6, 0
	s_cbranch_scc1 .Lmy_gb7_topspin
